# lever 2: P10a prologue: first query-fragment loads issued before waiting on the sub-key table loads (LDS fill after both are in flight)
# baseline (speedup 1.0000x reference)
; #define LAS __attribute__((address_space(3)))
;     ...
;     __syncthreads();
;     for (int i = F.tid; i < 256 * 16; i += NTHREADS) *(LAS u32x4*)(skl + (i >> 4) * 272 + (i & 15) * 16) = *(const u32x4*)(SK + (size_t)(i >> 4) * 128 + (i & 15) * 8);
;     bf16x8 qf[8];
;     if (F.bx < NTOK / 32) {
;         const bf16* qp = Q + (size_t)(F.bx * 32 + t) * D + head * 256 + 8 * hh;
; #pragma unroll
;         for (int ks = 0; ks < 8; ++ks) qf[ks] = *(const bf16x8*)(qp + 16 * ks);
;     }
.LBB0_1921:
	s_or_b64 exec, exec, s[6:7]
	s_waitcnt lgkmcnt(0)
	s_barrier
	v_mbcnt_lo_u32_b32 v3, -1, 0
	v_mbcnt_hi_u32_b32 v3, -1, v3
	s_nop 0
	v_add_u32_e32 v4, s3, v3
	s_movk_i32 s3, 0x1000
	v_cmp_gt_i32_e32 vcc, s3, v4
	s_barrier
	s_and_saveexec_b64 s[6:7], vcc
	s_cbranch_execz .LBB0_1924
	v_and_b32_e32 v0, 15, v3
	v_lshrrev_b32_e32 v1, 4, v4
	v_lshlrev_b32_e32 v0, 4, v0
	s_movk_i32 s3, 0x110
	v_lshl_add_u32 v2, v1, 8, v0
	v_mad_u32_u24 v39, v1, s3, v0
	s_add_u32 s8, s56, 0x3e00000
	s_addc_u32 s9, s57, 0
	global_load_dwordx4 v[6:9], v2, s[8:9]
	s_add_u32 s8, s8, 0x2000
	s_addc_u32 s9, s9, 0
	global_load_dwordx4 v[10:13], v2, s[8:9]
	s_add_u32 s8, s8, 0x2000
	s_addc_u32 s9, s9, 0
	global_load_dwordx4 v[14:17], v2, s[8:9]
	s_add_u32 s8, s8, 0x2000
	s_addc_u32 s9, s9, 0
	global_load_dwordx4 v[18:21], v2, s[8:9]
	s_add_u32 s8, s8, 0x2000
	s_addc_u32 s9, s9, 0
	global_load_dwordx4 v[22:25], v2, s[8:9]
	s_add_u32 s8, s8, 0x2000
	s_addc_u32 s9, s9, 0
	global_load_dwordx4 v[26:29], v2, s[8:9]
	s_add_u32 s8, s8, 0x2000
	s_addc_u32 s9, s9, 0
	global_load_dwordx4 v[30:33], v2, s[8:9]
	s_add_u32 s8, s8, 0x2000
	s_addc_u32 s9, s9, 0
	global_load_dwordx4 v[34:37], v2, s[8:9]
	s_add_u32 s8, s8, 0x2000
	s_addc_u32 s9, s9, 0
	v_add_u32_e32 v38, 0x8800, v39
.LBB0_1924:
	s_or_b64 exec, exec, s[6:7]
	s_add_u32 s6, s56, 0x26000000
	v_ashrrev_i32_e32 v0, 5, v3
	s_addc_u32 s7, s57, 0
	v_and_b32_e32 v98, 31, v3
	s_and_b64 vcc, exec, s[10:11]
	v_lshlrev_b32_e32 v96, 3, v0
	s_cbranch_vccz .Lmy_skl_noq
	v_lshl_or_b32 v4, s2, 5, v98
	v_ashrrev_i32_e32 v5, 31, v4
	v_lshlrev_b64 v[4:5], 12, v[4:5]
	v_lshl_add_u64 v[4:5], s[6:7], 0, v[4:5]
	s_lshl_b32 s8, s95, 9
	s_mov_b32 s9, 0
	v_lshl_add_u64 v[4:5], v[4:5], 0, s[8:9]
	v_ashrrev_i32_e32 v97, 31, v96
	v_lshl_add_u64 v[4:5], v[96:97], 1, v[4:5]
	global_load_dwordx4 v[64:67], v[4:5], off
	global_load_dwordx4 v[68:71], v[4:5], off offset:32
	global_load_dwordx4 v[72:75], v[4:5], off offset:64
	global_load_dwordx4 v[76:79], v[4:5], off offset:96
	global_load_dwordx4 v[80:83], v[4:5], off offset:128
	global_load_dwordx4 v[84:87], v[4:5], off offset:160
	global_load_dwordx4 v[88:91], v[4:5], off offset:192
	global_load_dwordx4 v[92:95], v[4:5], off offset:224
	s_waitcnt vmcnt(8)
	s_branch .Lmy_skl_w

; #define LAS __attribute__((address_space(3)))
;     ...
;     for (int i = F.tid; i < 256 * 16; i += NTHREADS) *(LAS u32x4*)(skl + (i >> 4) * 272 + (i & 15) * 16) = *(const u32x4*)(SK + (size_t)(i >> 4) * 128 + (i & 15) * 8);
.Lmy_skl_w:
	ds_write_b128 v39, v[6:9] offset:33792
	ds_write_b128 v39, v[10:13] offset:42496
	ds_write_b128 v39, v[14:17] offset:51200
	ds_write_b128 v39, v[18:21] offset:59904
	ds_write_b128 v38, v[22:25] offset:33792
	ds_write_b128 v38, v[26:29] offset:42496
	ds_write_b128 v38, v[30:33] offset:51200
	ds_write_b128 v38, v[34:37] offset:59904
